# spin loops of the LDS-polling group barriers run at s_setprio 0, rest at prio 1
# baseline (speedup 1.0000x reference)
.LBB0_308:
	v_mov_b32_e32 v0, s33
	s_setprio 0
	ds_read_b32 v0, v0 offset:8
	s_waitcnt lgkmcnt(0)
	v_cmp_gt_u32_e32 vcc, s0, v0
	s_cbranch_vccnz .LBB0_308
	s_setprio 1

.LBB0_893:
	v_mov_b32_e32 v0, s33
	s_setprio 0
	ds_read_b32 v0, v0 offset:8
	s_waitcnt lgkmcnt(0)
	v_cmp_gt_u32_e32 vcc, s0, v0
	s_cbranch_vccnz .LBB0_893
	s_setprio 1
	s_branch .LBB0_290

.LBB0_1048:
	v_mov_b32_e32 v6, s33
	s_setprio 0
	ds_read_b32 v6, v6 offset:8
	s_waitcnt lgkmcnt(0)
	v_cmp_gt_u32_e32 vcc, s8, v6
	s_cbranch_vccnz .LBB0_1048
	s_setprio 1

.LBB0_1053:
	v_mov_b32_e32 v0, s33
	s_setprio 0
	ds_read_b32 v0, v0 offset:8
	s_waitcnt lgkmcnt(0)
	v_cmp_gt_u32_e32 vcc, s20, v0
	s_cbranch_vccnz .LBB0_1053
	s_setprio 1

.LBB0_1355:
	v_mov_b32_e32 v4, s33
	s_setprio 0
	ds_read_b32 v4, v4 offset:8
	s_waitcnt lgkmcnt(0)
	v_cmp_gt_u32_e32 vcc, s14, v4
	s_cbranch_vccnz .LBB0_1355
	s_setprio 1

.LBB0_1360:
	v_mov_b32_e32 v0, s33
	s_setprio 0
	ds_read_b32 v0, v0 offset:8
	s_waitcnt lgkmcnt(0)
	v_cmp_gt_u32_e32 vcc, s14, v0
	s_cbranch_vccnz .LBB0_1360
	s_setprio 1

.LBB0_1365:
	v_mov_b32_e32 v5, s33
	s_setprio 0
	ds_read_b32 v5, v5 offset:8
	s_waitcnt lgkmcnt(0)
	v_cmp_gt_u32_e32 vcc, s31, v5
	s_cbranch_vccnz .LBB0_1365
	s_setprio 1

.LBB0_1377:
	v_mov_b32_e32 v0, s33
	s_setprio 0
	ds_read_b32 v0, v0 offset:8
	s_waitcnt lgkmcnt(0)
	v_cmp_gt_u32_e32 vcc, s17, v0
	s_cbranch_vccnz .LBB0_1377
	s_setprio 1

.LBB0_1390:
	v_mov_b32_e32 v0, s33
	s_setprio 0
	ds_read_b32 v0, v0 offset:8
	s_waitcnt lgkmcnt(0)
	v_cmp_gt_u32_e32 vcc, s4, v0
	s_cbranch_vccnz .LBB0_1390
	s_setprio 1

.LBB0_1397:
	v_mov_b32_e32 v4, s33
	s_setprio 0
	ds_read_b32 v4, v4 offset:8
	s_waitcnt lgkmcnt(0)
	v_cmp_gt_u32_e32 vcc, s4, v4
	s_cbranch_vccnz .LBB0_1397
	s_setprio 1

.LBB0_1407:
	v_mov_b32_e32 v5, s33
	s_setprio 0
	ds_read_b32 v5, v5 offset:8
	s_waitcnt lgkmcnt(0)
	v_cmp_gt_u32_e32 vcc, s81, v5
	s_cbranch_vccnz .LBB0_1407
	s_setprio 1

.LBB0_1432:
	v_mov_b32_e32 v0, s33
	s_setprio 0
	ds_read_b32 v0, v0 offset:8
	s_waitcnt lgkmcnt(0)
	v_cmp_gt_u32_e32 vcc, s81, v0
	s_cbranch_vccnz .LBB0_1432
	s_setprio 1
